# GEMM phase prologue de-serialisation: the b=1 half-tile stages are issued before the first certification wait (vmcnt(2)+barrier -> vmcnt(8)+barrier behind them) in all 12 GEMM phases; on top of non-sc
# speedup vs baseline: 1.0046x; 1.0046x over previous
.LBB0_238:
	s_add_i32 s53, s2, 0x18000
	s_and_b32 s18, s12, 3
	s_add_i32 s54, s53, s15
	s_mov_b64 s[12:13], 0x80
	s_lshl_b32 s19, s14, 13
	s_lshl_b32 s20, s18, 12
	v_lshl_add_u64 v[8:9], v[8:9], 0, s[12:13]
	s_mov_b32 m0, s54
	s_add_i32 s55, s54, 0x2000
	s_add_i32 s56, s49, 0x8000
	s_add_i32 s57, s49, 0xa000
	global_load_lds_dwordx4 v[8:9], off
	v_lshl_add_u64 v[6:7], v[6:7], 0, s[12:13]
	s_mov_b32 m0, s55
	s_add_u32 s16, s30, 0x40080
	global_load_lds_dwordx4 v[6:7], off
	v_lshl_add_u64 v[2:3], v[2:3], 0, s[12:13]
	s_mov_b32 m0, s56
	s_addc_u32 s17, s31, 0
	s_add_i32 s58, s2, 0x1c000
	global_load_lds_dwordx4 v[2:3], off
	v_lshl_add_u64 v[2:3], v[4:5], 0, s[12:13]
	s_mov_b32 m0, s57
	s_add_i32 s59, s58, s15
	global_load_lds_dwordx4 v[2:3], off
	v_lshl_add_u64 v[2:3], s[16:17], 0, v[196:197]
	s_mov_b32 m0, s59
	s_add_i32 s60, s59, 0x2000
	global_load_lds_dwordx4 v[2:3], off
	v_lshl_add_u64 v[2:3], s[16:17], 0, v[200:201]
	s_mov_b32 m0, s60
	s_mov_b64 s[16:17], 0x17600000
	global_load_lds_dwordx4 v[2:3], off
	v_bfe_u32 v3, v10, 4, 2
	v_and_b32_e32 v2, 15, v10
	v_lshlrev_b32_e32 v4, 3, v3
	v_lshlrev_b32_e32 v3, 4, v3
	v_lshl_or_b32 v1, s14, 6, v2
	v_lshl_or_b32 v2, v2, 6, v3
	v_lshlrev_b32_e32 v3, 2, v10
	v_and_b32_e32 v3, 32, v3
	v_bitop3_b32 v5, v2, s19, v3 bitop3:0xde
	v_bitop3_b32 v205, v2, s20, v3 bitop3:0xde
	v_bfe_i32 v2, v10, 4, 1
	v_lshlrev_b32_e32 v202, 1, v3
	v_and_b32_e32 v206, 24, v2
	v_lshl_add_u64 v[2:3], s[8:9], 0, v[202:203]
	v_lshl_add_u64 v[208:209], v[2:3], 0, s[16:17]
	v_lshrrev_b32_e32 v3, 1, v15
	v_mul_lo_u32 v2, v17, s0
	s_mov_b32 s63, 0x53000
	v_mad_u64_u32 v[2:3], s[16:17], v3, s63, v[2:3]
	v_or_b32_e32 v2, v2, v16
	v_add_lshl_u32 v202, v2, v18, 1
	v_lshrrev_b32_e32 v3, 1, v11
	v_mul_lo_u32 v2, v12, s0
	v_lshl_or_b32 v231, s18, 6, v4
	v_mad_u64_u32 v[2:3], s[18:19], v3, s63, v[2:3]
	s_waitcnt vmcnt(8)
	s_barrier
	s_waitcnt vmcnt(6)
	s_mov_b64 s[16:17], 0x530080
	v_or_b32_e32 v2, v2, v13
	s_cmpk_lt_u32 s3, 0x100
	v_lshl_add_u64 v[210:211], v[202:203], 0, s[16:17]
	v_add_lshl_u32 v202, v2, v14, 1
	s_cselect_b64 s[14:15], -1, 0
	v_and_b32_e32 v204, 8, v10
	s_mov_b32 s34, 0
	v_mov_b32_e32 v207, v203
	s_ashr_i32 s61, s33, 31
	s_ashr_i32 s62, s40, 31
	v_lshl_add_u64 v[212:213], v[202:203], 0, s[16:17]
	v_mov_b64_e32 v[214:215], 0x1518
	v_mov_b64_e32 v[216:217], 0x1517
	s_movk_i32 s64, 0x2a4
	v_add_u32_e32 v232, s1, v205
	v_add_u32_e32 v233, s5, v205
	v_add_u32_e32 v234, s2, v5
	v_mov_b32_e32 v235, 0x7f7f7f7f
	s_movk_i32 s65, 0x163f
	s_movk_i32 s66, 0x1e3f
	s_movk_i32 s67, 0x2640
	s_movk_i32 s68, 0x1800
	s_movk_i32 s69, 0x800
	s_movk_i32 s70, 0x1a00
	s_mov_b32 s71, 0xa600
	s_movk_i32 s72, 0x200
	s_mov_b64 s[16:17], 0x460fe9c0
	s_movk_i32 s73, 0xf7ff
	s_mov_b64 s[18:19], 0x12dfe1c0
	s_mov_b64 s[20:21], 0x151fcfc0
	s_mov_b64 s[22:23], 0x17603240
	s_movk_i32 s74, 0xf00
	v_mov_b32_e32 v236, 0x3c800000
	v_mov_b32_e32 v237, 0xbcb8aa3b
	v_mov_b32_e32 v238, 0x800
	v_mov_b32_e32 v239, 0xa600
	v_mov_b32_e32 v240, 0x200
	s_barrier
	s_branch .LBB0_241

.LBB0_408:
	s_add_u32 s8, s10, 0xe600000
	s_addc_u32 s9, s11, 0
	s_add_u32 s10, s10, 0x10a00000
	s_addc_u32 s11, s11, 0
	s_lshl_b32 s12, s12, 5
	s_add_i32 s58, s3, 0x18000
	s_and_b32 s20, s12, 0x60
	s_add_i32 s59, s58, s7
	s_mov_b64 s[12:13], 0x80
	s_lshl_b32 s16, s6, 13
	s_lshl_b32 s21, s20, 7
	v_lshl_add_u64 v[8:9], v[8:9], 0, s[12:13]
	s_mov_b32 m0, s59
	s_add_i32 s60, s59, 0x2000
	s_add_i32 s61, s54, 0x8000
	s_add_i32 s62, s54, 0xa000
	global_load_lds_dwordx4 v[8:9], off
	v_lshl_add_u64 v[6:7], v[6:7], 0, s[12:13]
	s_mov_b32 m0, s60
	s_add_u32 s14, s36, 0x10080
	global_load_lds_dwordx4 v[6:7], off
	v_lshl_add_u64 v[2:3], v[2:3], 0, s[12:13]
	s_mov_b32 m0, s61
	s_addc_u32 s15, s37, 0
	s_add_i32 s63, s3, 0x1c000
	global_load_lds_dwordx4 v[2:3], off
	v_lshl_add_u64 v[2:3], v[4:5], 0, s[12:13]
	s_mov_b32 m0, s62
	s_add_i32 s64, s63, s7
	global_load_lds_dwordx4 v[2:3], off
	v_lshl_add_u64 v[2:3], s[14:15], 0, v[198:199]
	s_mov_b32 m0, s64
	s_add_i32 s65, s64, 0x2000
	global_load_lds_dwordx4 v[2:3], off
	v_lshl_add_u64 v[2:3], s[14:15], 0, v[194:195]
	s_mov_b32 m0, s65
	v_bfe_u32 v1, v10, 4, 2
	global_load_lds_dwordx4 v[2:3], off
	s_sext_i32_i8 s67, s2
	v_lshlrev_b32_e32 v2, 3, v1
	v_lshlrev_b32_e32 v1, 4, v1
	v_lshlrev_b32_e32 v3, 6, v10
	s_movk_i32 s2, 0x3c0
	v_and_or_b32 v1, v3, s2, v1
	v_lshlrev_b32_e32 v3, 2, v10
	v_and_b32_e32 v3, 32, v3
	v_bitop3_b32 v4, v1, s16, v3 bitop3:0xde
	v_bitop3_b32 v1, v1, s21, v3 bitop3:0xde
	s_cmpk_lt_u32 s4, 0x100
	v_and_b32_e32 v3, 16, v10
	s_waitcnt vmcnt(8)
	s_barrier
	s_waitcnt vmcnt(6)
	s_cselect_b64 s[14:15], -1, 0
	v_cmp_ne_u32_e32 vcc, 0, v3
	s_ashr_i32 s66, s33, 31
	s_mov_b32 s4, 0
	v_cndmask_b32_e64 v3, 0, -8, vcc
	v_and_b32_e32 v5, 31, v10
	s_add_u32 s16, s33, s5
	v_lshl_or_b32 v214, s6, 6, v5
	v_add3_u32 v215, v2, v3, s20
	s_addc_u32 s17, s66, s17
	v_mov_b64_e32 v[202:203], 0x480
	v_mov_b64_e32 v[204:205], 0x47f
	v_add_u32_e32 v216, s18, v1
	v_add_u32_e32 v217, s19, v1
	v_add_u32_e32 v218, s3, v4
	s_mov_b32 s5, s4
	s_mov_b32 s6, s4
	s_mov_b32 s7, s4
	v_mov_b32_e32 v219, 0x7f7f7f7f
	s_mov_b64 s[18:19], 0x100
	s_mov_b64 s[20:21], 0x180
	s_mov_b32 s22, 0x3d000000
	s_mov_b64 s[24:25], 0x40000
	s_mov_b64 s[26:27], 0x50000
	v_mov_b32_e32 v220, v199
	s_barrier
	s_branch .LBB0_411

.LBB0_873:
	s_add_u32 s44, s12, 0x17600000
	s_addc_u32 s45, s13, 0
	s_add_u32 s10, s12, 0xe600000
	s_addc_u32 s11, s13, 0
	s_add_u32 s46, s12, 0x17606480
	s_addc_u32 s47, s13, 0
	s_add_u32 s12, s12, 0x12e00000
	s_addc_u32 s13, s13, 0
	s_lshl_b32 s14, s14, 5
	s_add_i32 s48, s2, 0x18000
	s_and_b32 s23, s14, 0x60
	s_add_i32 s49, s48, s18
	s_mov_b64 s[14:15], 0x80
	s_lshl_b32 s19, s0, 13
	s_lshl_b32 s26, s23, 7
	v_lshl_add_u64 v[8:9], v[8:9], 0, s[14:15]
	s_mov_b32 m0, s49
	s_add_i32 s50, s49, 0x2000
	s_add_i32 s51, s40, 0x8000
	s_add_i32 s52, s40, 0xa000
	global_load_lds_dwordx4 v[8:9], off
	v_lshl_add_u64 v[6:7], v[6:7], 0, s[14:15]
	s_mov_b32 m0, s50
	s_mov_b64 s[16:17], 0x100
	s_add_u32 s24, s6, 0x40080
	global_load_lds_dwordx4 v[6:7], off
	v_lshl_add_u64 v[2:3], v[2:3], 0, s[16:17]
	s_mov_b32 m0, s51
	s_addc_u32 s25, s7, 0
	s_add_i32 s53, s2, 0x1c000
	global_load_lds_dwordx4 v[2:3], off
	v_lshl_add_u64 v[2:3], v[4:5], 0, s[16:17]
	s_mov_b32 m0, s52
	s_add_i32 s54, s53, s18
	global_load_lds_dwordx4 v[2:3], off
	v_lshl_add_u64 v[2:3], s[24:25], 0, v[196:197]
	s_mov_b32 m0, s54
	s_add_i32 s55, s54, 0x2000
	global_load_lds_dwordx4 v[2:3], off
	v_lshl_add_u64 v[2:3], s[24:25], 0, v[200:201]
	s_mov_b32 m0, s55
	s_cmpk_lt_u32 s3, 0x100
	global_load_lds_dwordx4 v[2:3], off
	v_lshrrev_b32_e32 v3, 1, v10
	v_and_b32_e32 v3, 24, v3
	v_and_b32_e32 v2, 15, v10
	v_lshlrev_b32_e32 v4, 1, v3
	v_lshl_or_b32 v1, s0, 6, v2
	v_lshl_or_b32 v2, v2, 6, v4
	v_lshlrev_b32_e32 v4, 2, v10
	v_and_b32_e32 v4, 32, v4
	v_bitop3_b32 v5, v2, s19, v4 bitop3:0xde
	v_bitop3_b32 v222, v2, s26, v4 bitop3:0xde
	v_or_b32_e32 v223, s23, v3
	v_lshrrev_b32_e32 v3, 1, v15
	v_mul_lo_u32 v2, v17, s1
	s_mov_b32 s0, 0x53000
	v_mad_u64_u32 v[2:3], s[24:25], v3, s0, v[2:3]
	v_or_b32_e32 v2, v2, v16
	v_add_lshl_u32 v2, v2, v18, 1
	v_mov_b32_e32 v3, v197
	s_mov_b64 s[24:25], 0x530100
	v_lshl_add_u64 v[202:203], v[2:3], 0, s[24:25]
	v_lshrrev_b32_e32 v3, 1, v11
	v_mul_lo_u32 v2, v12, s1
	v_mad_u64_u32 v[2:3], s[0:1], v3, s0, v[2:3]
	s_waitcnt vmcnt(8)
	s_barrier
	s_waitcnt vmcnt(6)
	v_or_b32_e32 v2, v2, v13
	v_add_lshl_u32 v2, v2, v14, 1
	v_mov_b32_e32 v3, v197
	s_cselect_b64 s[18:19], -1, 0
	s_ashr_i32 s56, s33, 31
	v_lshl_add_u64 v[204:205], v[2:3], 0, s[24:25]
	s_mov_b32 s63, 0
	v_mov_b64_e32 v[206:207], 0x240
	v_mov_b64_e32 v[208:209], 0x23f
	s_movk_i32 s57, 0x49
	v_add_u32_e32 v224, s20, v222
	v_add_u32_e32 v225, s22, v222
	v_add_u32_e32 v226, s2, v5
	v_mov_b32_e32 v227, 0x7f7f7f7f
	s_mov_b32 s58, 0xa600
	s_mov_b32 s20, 0x3a800000
	s_mov_b32 s26, 0
	s_barrier
	s_branch .LBB0_876

.LBB0_1052:
	s_add_u32 s4, s4, 0x17600000
	s_addc_u32 s5, s5, 0
	s_lshl_b32 s6, s6, 5
	s_add_i32 s58, s3, 0x18000
	s_and_b32 s17, s6, 0x60
	s_add_i32 s59, s58, s10
	s_mov_b64 s[6:7], 0x80
	s_lshl_b32 s16, s9, 13
	s_lshl_b32 s18, s17, 7
	v_lshl_add_u64 v[8:9], v[8:9], 0, s[6:7]
	s_mov_b32 m0, s59
	s_add_i32 s60, s59, 0x2000
	s_add_i32 s61, s54, 0x8000
	s_add_i32 s62, s54, 0xa000
	global_load_lds_dwordx4 v[8:9], off
	v_lshl_add_u64 v[6:7], v[6:7], 0, s[6:7]
	s_mov_b32 m0, s60
	s_add_u32 s14, s36, 0x40080
	global_load_lds_dwordx4 v[6:7], off
	v_lshl_add_u64 v[2:3], v[2:3], 0, s[6:7]
	s_mov_b32 m0, s61
	s_addc_u32 s15, s37, 0
	s_add_i32 s63, s3, 0x1c000
	global_load_lds_dwordx4 v[2:3], off
	v_lshl_add_u64 v[2:3], v[4:5], 0, s[6:7]
	s_mov_b32 m0, s62
	s_add_i32 s64, s63, s10
	global_load_lds_dwordx4 v[2:3], off
	v_lshl_add_u64 v[2:3], s[14:15], 0, v[198:199]
	s_mov_b32 m0, s64
	s_add_i32 s65, s64, 0x2000
	global_load_lds_dwordx4 v[2:3], off
	v_lshl_add_u64 v[2:3], s[14:15], 0, v[194:195]
	s_mov_b32 m0, s65
	s_mov_b64 s[14:15], 0x40080
	global_load_lds_dwordx4 v[2:3], off
	v_lshrrev_b32_e32 v3, 1, v10
	v_and_b32_e32 v3, 24, v3
	v_and_b32_e32 v2, 15, v10
	v_lshlrev_b32_e32 v4, 1, v3
	v_lshl_or_b32 v1, s9, 6, v2
	v_lshl_or_b32 v2, v2, 6, v4
	v_lshlrev_b32_e32 v4, 2, v10
	v_and_b32_e32 v4, 32, v4
	v_bitop3_b32 v5, v2, s16, v4 bitop3:0xde
	v_bitop3_b32 v222, v2, s18, v4 bitop3:0xde
	v_lshlrev_b32_e32 v2, 14, v11
	v_and_b32_e32 v2, 0xffff8000, v2
	v_or_b32_e32 v223, s17, v3
	v_lshl_add_u32 v2, v12, 11, v2
	v_and_b32_e32 v3, 1, v11
	v_lshl_or_b32 v2, v3, 6, v2
	v_lshl_add_u32 v2, v13, 1, v2
	v_mov_b32_e32 v3, v199
	v_lshl_add_u64 v[202:203], v[2:3], 0, s[14:15]
	v_lshlrev_b32_e32 v2, 14, v15
	v_and_b32_e32 v2, 0xffff8000, v2
	v_lshl_add_u32 v2, v14, 11, v2
	v_and_b32_e32 v3, 1, v15
	s_waitcnt vmcnt(8)
	s_barrier
	s_waitcnt vmcnt(6)
	v_lshl_or_b32 v2, v3, 6, v2
	s_cmpk_lt_u32 s8, 0x100
	v_lshl_add_u32 v2, v16, 1, v2
	v_mov_b32_e32 v3, v199
	s_sext_i32_i8 s72, s2
	s_cselect_b64 s[8:9], -1, 0
	s_ashr_i32 s66, s33, 31
	v_lshl_add_u64 v[204:205], v[2:3], 0, s[14:15]
	s_mov_b32 s34, 0
	v_mov_b64_e32 v[206:207], 0x240
	v_mov_b64_e32 v[208:209], 0x23f
	v_add_u32_e32 v224, s12, v222
	v_add_u32_e32 v225, s13, v222
	v_add_u32_e32 v226, s3, v5
	v_mov_b32_e32 v227, 0x7f7f7f7f
	s_mov_b32 s10, 0x3a000000
	s_mov_b64 s[12:13], 0x80000
	s_mov_b32 s67, 0x80000
	s_mov_b64 s[14:15], 0x90000
	s_mov_b32 s68, 0x90000
	s_mov_b64 s[16:17], 0xa0000
	s_mov_b32 s69, 0xa0000
	s_mov_b64 s[18:19], 0xb0000
	s_mov_b32 s70, 0xb0000
	s_barrier
	s_branch .LBB0_1055

.LBB0_1215:
	s_add_u32 s20, s5, 0x30200000
	s_addc_u32 s21, s6, 0
	s_add_u32 s22, s5, 0x17600000
	s_addc_u32 s23, s6, 0
	s_add_u32 s72, s5, 0x18600000
	s_addc_u32 s73, s6, 0
	s_lshl_b32 s3, s3, 5
	s_add_i32 s74, s14, 0x18000
	s_and_b32 s35, s3, 0x60
	s_add_i32 s75, s74, s2
	s_mov_b64 s[24:25], 0x80
	s_lshl_b32 s5, s63, 6
	s_lshl_b32 s8, s63, 13
	s_lshl_b32 s3, s35, 7
	v_lshl_add_u64 v[8:9], v[8:9], 0, s[24:25]
	s_mov_b32 m0, s75
	s_add_i32 s76, s75, 0x2000
	s_add_i32 s77, s68, 0x8000
	s_add_i32 s78, s68, 0xa000
	global_load_lds_dwordx4 v[8:9], off
	v_lshl_add_u64 v[6:7], v[6:7], 0, s[24:25]
	s_mov_b32 m0, s76
	s_add_u32 s6, s50, 0x80080
	global_load_lds_dwordx4 v[6:7], off
	v_lshl_add_u64 v[2:3], v[2:3], 0, s[24:25]
	s_mov_b32 m0, s77
	s_addc_u32 s7, s51, 0
	s_add_i32 s79, s14, 0x1c000
	global_load_lds_dwordx4 v[2:3], off
	v_lshl_add_u64 v[2:3], v[4:5], 0, s[24:25]
	s_mov_b32 m0, s78
	s_add_i32 s80, s79, s2
	global_load_lds_dwordx4 v[2:3], off
	v_lshl_add_u64 v[2:3], s[6:7], 0, v[196:197]
	s_mov_b32 m0, s80
	s_add_i32 s81, s80, 0x2000
	global_load_lds_dwordx4 v[2:3], off
	v_lshl_add_u64 v[2:3], s[6:7], 0, v[200:201]
	s_mov_b32 m0, s81
	v_and_b32_e32 v202, 15, v1
	global_load_lds_dwordx4 v[2:3], off
	v_lshrrev_b32_e32 v2, 1, v1
	v_and_b32_e32 v2, 24, v2
	v_lshlrev_b32_e32 v3, 1, v2
	v_lshlrev_b32_e32 v1, 2, v1
	v_or_b32_e32 v203, s35, v2
	v_lshlrev_b32_e32 v2, 15, v13
	v_lshl_or_b32 v3, v202, 6, v3
	v_and_b32_e32 v1, 32, v1
	v_and_b32_e32 v2, 0xffff0000, v2
	v_bitop3_b32 v4, v3, s8, v1 bitop3:0xde
	v_bitop3_b32 v1, v3, s3, v1 bitop3:0xde
	v_lshl_add_u32 v2, v14, 12, v2
	v_and_b32_e32 v3, 1, v13
	v_lshl_or_b32 v2, v3, 6, v2
	s_mov_b64 s[36:37], 0x80080
	v_lshl_add_u32 v2, v15, 1, v2
	v_mov_b32_e32 v3, v197
	s_cmpk_lt_u32 s4, 0x100
	v_lshl_add_u64 v[208:209], v[2:3], 0, s[36:37]
	v_lshlrev_b32_e32 v2, 15, v10
	s_cselect_b64 s[26:27], -1, 0
	s_ashr_i32 s2, s5, 31
	s_ashr_i32 s82, s33, 31
	s_ashr_i32 s83, s58, 31
	v_and_b32_e32 v2, 0xffff0000, v2
	s_add_u32 s28, s0, 0x5800
	v_lshl_add_u32 v2, v11, 12, v2
	v_and_b32_e32 v3, 1, v10
	s_waitcnt vmcnt(8)
	s_barrier
	s_waitcnt vmcnt(6)
	s_addc_u32 s29, s1, 0
	v_lshl_or_b32 v2, v3, 6, v2
	s_add_u32 s30, s0, 0xb000
	v_lshl_add_u32 v2, v12, 1, v2
	v_mov_b32_e32 v3, v197
	v_or_b32_e32 v204, s5, v202
	v_mov_b32_e32 v205, s2
	v_cmp_eq_u32_e64 s[2:3], 15, v202
	s_mov_b32 s48, 0
	v_cmp_eq_u32_e64 s[4:5], 0, v202
	v_cmp_ne_u32_e64 s[6:7], 15, v202
	v_cmp_ne_u32_e64 s[8:9], 0, v202
	v_cmp_gt_u32_e64 s[10:11], 2, v202
	v_cmp_lt_u32_e64 s[12:13], 13, v202
	v_add_u32_e32 v206, -12, v202
	v_mov_b32_e32 v207, v197
	s_addc_u32 s31, s1, 0
	v_lshl_add_u64 v[210:211], v[2:3], 0, s[36:37]
	v_mov_b64_e32 v[212:213], 0xc60
	v_mov_b64_e32 v[214:215], 0xc5f
	s_movk_i32 s84, 0x18d
	v_add_u32_e32 v228, s15, v1
	v_add_u32_e32 v229, s34, v1
	v_add_u32_e32 v231, s14, v4
	s_movk_i32 s85, 0x2c00
	s_mov_b32 s86, 0x2c000
	s_mov_b32 s87, 0x58000
	s_mov_b32 s88, 0x18c000
	s_mov_b32 s89, 0x1b8000
	v_mov_b32_e32 v232, 0x2c00
	s_barrier
	s_branch .LBB0_1218

.LBB0_1383:
	s_add_u32 s6, s6, 0xe600000
	s_addc_u32 s7, s7, 0
	s_lshl_b32 s8, s8, 5
	s_add_i32 s52, s0, 0x18000
	s_and_b32 s17, s8, 0x60
	s_add_i32 s53, s52, s10
	s_mov_b64 s[8:9], 0x80
	s_lshl_b32 s16, s3, 13
	s_lshl_b32 s18, s17, 7
	v_lshl_add_u64 v[8:9], v[8:9], 0, s[8:9]
	s_mov_b32 m0, s53
	s_add_i32 s54, s53, 0x2000
	s_add_i32 s55, s48, 0x8000
	s_add_i32 s56, s48, 0xa000
	global_load_lds_dwordx4 v[8:9], off
	v_lshl_add_u64 v[6:7], v[6:7], 0, s[8:9]
	s_mov_b32 m0, s54
	s_add_u32 s14, s26, 0x160080
	global_load_lds_dwordx4 v[6:7], off
	v_lshl_add_u64 v[2:3], v[2:3], 0, s[8:9]
	s_mov_b32 m0, s55
	s_addc_u32 s15, s27, 0
	s_add_i32 s57, s0, 0x1c000
	global_load_lds_dwordx4 v[2:3], off
	v_lshl_add_u64 v[2:3], v[4:5], 0, s[8:9]
	s_mov_b32 m0, s56
	s_add_i32 s58, s57, s10
	global_load_lds_dwordx4 v[2:3], off
	v_lshl_add_u64 v[2:3], s[14:15], 0, v[198:199]
	s_mov_b32 m0, s58
	s_add_i32 s59, s58, 0x2000
	global_load_lds_dwordx4 v[2:3], off
	v_lshl_add_u64 v[2:3], s[14:15], 0, v[194:195]
	s_mov_b32 m0, s59
	s_cmpk_lt_u32 s1, 0x100
	global_load_lds_dwordx4 v[2:3], off
	v_lshrrev_b32_e32 v3, 1, v10
	v_and_b32_e32 v3, 24, v3
	v_and_b32_e32 v2, 15, v10
	v_lshlrev_b32_e32 v4, 1, v3
	v_lshl_or_b32 v1, s3, 6, v2
	v_lshl_or_b32 v2, v2, 6, v4
	v_lshlrev_b32_e32 v4, 2, v10
	v_and_b32_e32 v4, 32, v4
	v_bitop3_b32 v5, v2, s16, v4 bitop3:0xde
	v_bitop3_b32 v222, v2, s18, v4 bitop3:0xde
	v_or_b32_e32 v223, s17, v3
	v_lshrrev_b32_e32 v3, 1, v11
	v_mul_lo_u32 v2, v12, s2
	s_mov_b32 s1, 0x16000
	v_mad_u64_u32 v[2:3], s[16:17], v3, s1, v[2:3]
	v_or_b32_e32 v2, v2, v13
	s_mov_b64 s[14:15], 0x160080
	v_add_lshl_u32 v2, v2, v14, 1
	v_mov_b32_e32 v3, v199
	v_lshl_add_u64 v[202:203], v[2:3], 0, s[14:15]
	v_lshrrev_b32_e32 v3, 1, v16
	v_mul_lo_u32 v2, v15, s2
	v_mad_u64_u32 v[2:3], s[2:3], v3, s1, v[2:3]
	s_waitcnt vmcnt(8)
	s_barrier
	s_waitcnt vmcnt(6)
	v_or_b32_e32 v2, v2, v17
	v_add_lshl_u32 v2, v2, v18, 1
	v_mov_b32_e32 v3, v199
	s_sext_i32_i8 s69, s11
	s_cselect_b64 s[10:11], -1, 0
	s_ashr_i32 s60, s36, 31
	v_lshl_add_u64 v[204:205], v[2:3], 0, s[14:15]
	s_mov_b32 s24, 0
	v_mov_b64_e32 v[206:207], 0x240
	v_mov_b64_e32 v[208:209], 0x23f
	v_add_u32_e32 v224, s12, v222
	v_add_u32_e32 v225, s13, v222
	v_add_u32_e32 v226, s0, v5
	s_mov_b64 s[12:13], 0x80000
	s_mov_b32 s61, 0x80000
	s_mov_b64 s[14:15], 0x90000
	s_mov_b32 s62, 0x90000
	s_mov_b64 s[16:17], 0xa0000
	s_mov_b32 s63, 0xa0000
	s_mov_b64 s[18:19], 0xb0000
	s_mov_b32 s64, 0xb0000
	s_barrier
	s_branch .LBB0_1386

.LBB0_1578:
	s_add_i32 s53, s16, 0x18000
	s_and_b32 s2, s2, 3
	s_add_i32 s54, s53, s17
	s_mov_b64 s[12:13], 0x80
	s_lshl_b32 s5, s15, 13
	s_lshl_b32 s20, s2, 12
	v_lshl_add_u64 v[8:9], v[8:9], 0, s[12:13]
	s_mov_b32 m0, s54
	s_add_i32 s55, s54, 0x2000
	s_add_i32 s56, s49, 0x8000
	s_add_i32 s57, s49, 0xa000
	global_load_lds_dwordx4 v[8:9], off
	v_lshl_add_u64 v[6:7], v[6:7], 0, s[12:13]
	s_mov_b32 m0, s55
	s_add_u32 s18, s30, 0x40080
	global_load_lds_dwordx4 v[6:7], off
	v_lshl_add_u64 v[2:3], v[2:3], 0, s[12:13]
	s_mov_b32 m0, s56
	s_addc_u32 s19, s31, 0
	s_add_i32 s58, s16, 0x1c000
	global_load_lds_dwordx4 v[2:3], off
	v_lshl_add_u64 v[2:3], v[4:5], 0, s[12:13]
	s_mov_b32 m0, s57
	s_add_i32 s59, s58, s17
	global_load_lds_dwordx4 v[2:3], off
	v_lshl_add_u64 v[2:3], s[18:19], 0, v[196:197]
	s_mov_b32 m0, s59
	s_add_i32 s60, s59, 0x2000
	global_load_lds_dwordx4 v[2:3], off
	v_lshl_add_u64 v[2:3], s[18:19], 0, v[200:201]
	s_mov_b32 m0, s60
	s_mov_b64 s[18:19], 0x17600000
	global_load_lds_dwordx4 v[2:3], off
	v_bfe_u32 v3, v10, 4, 2
	v_and_b32_e32 v2, 15, v10
	v_lshlrev_b32_e32 v4, 3, v3
	v_lshlrev_b32_e32 v3, 4, v3
	v_lshl_or_b32 v1, s15, 6, v2
	v_lshl_or_b32 v2, v2, 6, v3
	v_lshlrev_b32_e32 v3, 2, v10
	v_and_b32_e32 v3, 32, v3
	v_bitop3_b32 v5, v2, s5, v3 bitop3:0xde
	v_bitop3_b32 v205, v2, s20, v3 bitop3:0xde
	v_bfe_i32 v2, v10, 4, 1
	v_lshlrev_b32_e32 v202, 1, v3
	v_and_b32_e32 v206, 24, v2
	v_lshl_add_u64 v[2:3], s[8:9], 0, v[202:203]
	v_lshl_add_u64 v[208:209], v[2:3], 0, s[18:19]
	v_lshrrev_b32_e32 v3, 1, v15
	v_mul_lo_u32 v2, v17, s0
	s_mov_b32 s63, 0x53000
	v_mad_u64_u32 v[2:3], s[18:19], v3, s63, v[2:3]
	v_or_b32_e32 v2, v2, v16
	v_add_lshl_u32 v202, v2, v18, 1
	v_lshrrev_b32_e32 v3, 1, v11
	v_mul_lo_u32 v2, v12, s0
	v_mad_u64_u32 v[2:3], s[20:21], v3, s63, v[2:3]
	s_waitcnt vmcnt(8)
	s_barrier
	s_waitcnt vmcnt(6)
	s_mov_b64 s[18:19], 0x530080
	v_or_b32_e32 v2, v2, v13
	s_cmpk_lt_u32 s14, 0x100
	v_lshl_add_u64 v[210:211], v[202:203], 0, s[18:19]
	v_add_lshl_u32 v202, v2, v14, 1
	s_cselect_b64 s[14:15], -1, 0
	v_lshl_or_b32 v231, s2, 6, v4
	v_and_b32_e32 v204, 8, v10
	s_mov_b32 s34, 0
	v_mov_b32_e32 v207, v203
	s_ashr_i32 s61, s33, 31
	s_ashr_i32 s62, s40, 31
	v_lshl_add_u64 v[212:213], v[202:203], 0, s[18:19]
	v_mov_b64_e32 v[214:215], 0x1388
	v_mov_b64_e32 v[216:217], 0x1387
	s_movk_i32 s64, 0x272
	v_add_u32_e32 v232, s1, v205
	v_add_u32_e32 v233, s3, v205
	v_add_u32_e32 v234, s16, v5
	v_mov_b32_e32 v235, 0x7f7f7f7f
	s_movk_i32 s65, 0x163f
	s_movk_i32 s66, 0x1e3f
	s_movk_i32 s67, 0x2640
	s_movk_i32 s68, 0x1800
	s_movk_i32 s69, 0x800
	s_movk_i32 s70, 0x1a00
	s_mov_b32 s71, 0xa600
	s_movk_i32 s72, 0x200
	s_mov_b64 s[16:17], 0x460fe9c0
	s_movk_i32 s73, 0xf7ff
	s_mov_b64 s[18:19], 0x12dfe1c0
	s_mov_b64 s[20:21], 0x151fcfc0
	s_mov_b64 s[22:23], 0x17603240
	s_movk_i32 s74, 0xf00
	v_mov_b32_e32 v236, 0x3c800000
	v_mov_b32_e32 v237, 0xbcb8aa3b
	v_mov_b32_e32 v238, 0x800
	v_mov_b32_e32 v239, 0xa600
	v_mov_b32_e32 v240, 0x200
	s_barrier
	s_branch .LBB0_1581

.LBB0_2208:
	s_add_u32 s44, s12, 0x17600000
	s_addc_u32 s45, s13, 0
	s_add_u32 s10, s12, 0xe600000
	s_addc_u32 s11, s13, 0
	s_add_u32 s46, s12, 0x17606480
	s_addc_u32 s47, s13, 0
	s_add_u32 s12, s12, 0x12e00000
	s_addc_u32 s13, s13, 0
	s_lshl_b32 s14, s14, 5
	s_add_i32 s48, s20, 0x18000
	s_and_b32 s25, s14, 0x60
	s_add_i32 s49, s48, s19
	s_mov_b64 s[14:15], 0x80
	s_lshl_b32 s24, s0, 13
	s_lshl_b32 s26, s25, 7
	v_lshl_add_u64 v[8:9], v[8:9], 0, s[14:15]
	s_mov_b32 m0, s49
	s_add_i32 s50, s49, 0x2000
	s_add_i32 s51, s40, 0x8000
	s_add_i32 s52, s40, 0xa000
	global_load_lds_dwordx4 v[8:9], off
	v_lshl_add_u64 v[6:7], v[6:7], 0, s[14:15]
	s_mov_b32 m0, s50
	s_mov_b64 s[16:17], 0x100
	s_add_u32 s22, s6, 0x40080
	global_load_lds_dwordx4 v[6:7], off
	v_lshl_add_u64 v[2:3], v[2:3], 0, s[16:17]
	s_mov_b32 m0, s51
	s_addc_u32 s23, s7, 0
	s_add_i32 s53, s20, 0x1c000
	global_load_lds_dwordx4 v[2:3], off
	v_lshl_add_u64 v[2:3], v[4:5], 0, s[16:17]
	s_mov_b32 m0, s52
	s_add_i32 s54, s53, s19
	global_load_lds_dwordx4 v[2:3], off
	v_lshl_add_u64 v[2:3], s[22:23], 0, v[196:197]
	s_mov_b32 m0, s54
	s_add_i32 s55, s54, 0x2000
	global_load_lds_dwordx4 v[2:3], off
	v_lshl_add_u64 v[2:3], s[22:23], 0, v[200:201]
	s_mov_b32 m0, s55
	s_cmpk_lt_u32 s18, 0x100
	global_load_lds_dwordx4 v[2:3], off
	v_lshrrev_b32_e32 v3, 1, v10
	v_and_b32_e32 v3, 24, v3
	v_and_b32_e32 v2, 15, v10
	v_lshlrev_b32_e32 v4, 1, v3
	v_lshl_or_b32 v1, s0, 6, v2
	v_lshl_or_b32 v2, v2, 6, v4
	v_lshlrev_b32_e32 v4, 2, v10
	v_and_b32_e32 v4, 32, v4
	v_bitop3_b32 v5, v2, s24, v4 bitop3:0xde
	v_bitop3_b32 v222, v2, s26, v4 bitop3:0xde
	v_or_b32_e32 v223, s25, v3
	v_lshrrev_b32_e32 v3, 1, v15
	v_mul_lo_u32 v2, v17, s1
	s_mov_b32 s0, 0x53000
	v_mad_u64_u32 v[2:3], s[22:23], v3, s0, v[2:3]
	v_or_b32_e32 v2, v2, v16
	v_add_lshl_u32 v2, v2, v18, 1
	v_mov_b32_e32 v3, v197
	s_mov_b64 s[22:23], 0x530100
	v_lshl_add_u64 v[202:203], v[2:3], 0, s[22:23]
	v_lshrrev_b32_e32 v3, 1, v11
	v_mul_lo_u32 v2, v12, s1
	v_mad_u64_u32 v[2:3], s[0:1], v3, s0, v[2:3]
	s_waitcnt vmcnt(8)
	s_barrier
	s_waitcnt vmcnt(6)
	v_or_b32_e32 v2, v2, v13
	v_add_lshl_u32 v2, v2, v14, 1
	v_mov_b32_e32 v3, v197
	s_cselect_b64 s[18:19], -1, 0
	s_ashr_i32 s56, s33, 31
	v_lshl_add_u64 v[204:205], v[2:3], 0, s[22:23]
	s_mov_b32 s62, 0
	v_mov_b64_e32 v[206:207], 0x200
	v_mov_b64_e32 v[208:209], 0x1ff
	v_add_u32_e32 v224, s2, v222
	v_add_u32_e32 v225, s3, v222
	v_add_u32_e32 v226, s20, v5
	v_mov_b32_e32 v227, 0x7f7f7f7f
	s_mov_b32 s57, 0xa600
	s_mov_b32 s20, 0x3a800000
	s_mov_b32 s26, 0
	s_barrier
	s_branch .LBB0_2211

.LBB0_2395:
	s_add_u32 s4, s4, 0x17600000
	s_addc_u32 s5, s5, 0
	s_lshl_b32 s6, s6, 5
	s_add_i32 s57, s3, 0x18000
	s_and_b32 s17, s6, 0x60
	s_add_i32 s58, s57, s13
	s_mov_b64 s[6:7], 0x80
	s_lshl_b32 s16, s9, 13
	s_lshl_b32 s18, s17, 7
	v_lshl_add_u64 v[8:9], v[8:9], 0, s[6:7]
	s_mov_b32 m0, s58
	s_add_i32 s59, s58, 0x2000
	s_add_i32 s60, s53, 0x8000
	s_add_i32 s61, s53, 0xa000
	global_load_lds_dwordx4 v[8:9], off
	v_lshl_add_u64 v[6:7], v[6:7], 0, s[6:7]
	s_mov_b32 m0, s59
	s_add_u32 s14, s36, 0x40080
	global_load_lds_dwordx4 v[6:7], off
	v_lshl_add_u64 v[2:3], v[2:3], 0, s[6:7]
	s_mov_b32 m0, s60
	s_addc_u32 s15, s37, 0
	s_add_i32 s62, s3, 0x1c000
	global_load_lds_dwordx4 v[2:3], off
	v_lshl_add_u64 v[2:3], v[4:5], 0, s[6:7]
	s_mov_b32 m0, s61
	s_add_i32 s63, s62, s13
	global_load_lds_dwordx4 v[2:3], off
	v_lshl_add_u64 v[2:3], s[14:15], 0, v[196:197]
	s_mov_b32 m0, s63
	s_add_i32 s64, s63, 0x2000
	global_load_lds_dwordx4 v[2:3], off
	v_lshl_add_u64 v[2:3], s[14:15], 0, v[200:201]
	s_mov_b32 m0, s64
	s_mov_b64 s[14:15], 0x40080
	global_load_lds_dwordx4 v[2:3], off
	v_lshrrev_b32_e32 v3, 1, v10
	v_and_b32_e32 v3, 24, v3
	v_and_b32_e32 v2, 15, v10
	v_lshlrev_b32_e32 v4, 1, v3
	v_lshl_or_b32 v1, s9, 6, v2
	v_lshl_or_b32 v2, v2, 6, v4
	v_lshlrev_b32_e32 v4, 2, v10
	v_and_b32_e32 v4, 32, v4
	v_bitop3_b32 v5, v2, s16, v4 bitop3:0xde
	v_bitop3_b32 v222, v2, s18, v4 bitop3:0xde
	v_lshlrev_b32_e32 v2, 14, v14
	v_and_b32_e32 v2, 0xffff8000, v2
	v_or_b32_e32 v223, s17, v3
	v_lshl_add_u32 v2, v15, 11, v2
	v_and_b32_e32 v3, 1, v14
	v_lshl_or_b32 v2, v3, 6, v2
	v_lshl_add_u32 v2, v16, 1, v2
	v_mov_b32_e32 v3, v197
	v_lshl_add_u64 v[202:203], v[2:3], 0, s[14:15]
	v_lshlrev_b32_e32 v2, 14, v11
	v_and_b32_e32 v2, 0xffff8000, v2
	v_lshl_add_u32 v2, v12, 11, v2
	v_and_b32_e32 v3, 1, v11
	s_waitcnt vmcnt(8)
	s_barrier
	s_waitcnt vmcnt(6)
	v_lshl_or_b32 v2, v3, 6, v2
	s_cmpk_lt_u32 s8, 0x100
	v_lshl_add_u32 v2, v13, 1, v2
	v_mov_b32_e32 v3, v197
	s_sext_i32_i8 s71, s2
	s_cselect_b64 s[8:9], -1, 0
	s_ashr_i32 s65, s33, 31
	v_lshl_add_u64 v[204:205], v[2:3], 0, s[14:15]
	s_mov_b32 s34, 0
	v_mov_b64_e32 v[206:207], 0x200
	v_mov_b64_e32 v[208:209], 0x1ff
	v_add_u32_e32 v224, s10, v222
	v_add_u32_e32 v225, s12, v222
	v_add_u32_e32 v226, s3, v5
	v_mov_b32_e32 v227, 0x7f7f7f7f
	s_mov_b32 s10, 0x3a000000
	s_mov_b64 s[12:13], 0x80000
	s_mov_b32 s66, 0x80000
	s_mov_b64 s[14:15], 0x90000
	s_mov_b32 s67, 0x90000
	s_mov_b64 s[16:17], 0xa0000
	s_mov_b32 s68, 0xa0000
	s_mov_b64 s[18:19], 0xb0000
	s_mov_b32 s69, 0xb0000
	s_barrier
	s_branch .LBB0_2398

.LBB0_2549:
	s_add_u32 s16, s3, 0x30200000
	s_addc_u32 s17, s4, 0
	s_add_u32 s18, s15, 0x10800
	s_addc_u32 s19, s31, 0
	s_add_u32 s20, s5, 0x5800
	s_addc_u32 s21, s6, 0
	s_add_u32 s22, s3, 0x17600000
	s_addc_u32 s23, s4, 0
	s_add_u32 s72, s3, 0x18600000
	s_addc_u32 s73, s4, 0
	s_lshl_b32 s4, s8, 5
	s_add_i32 s74, s14, 0x18000
	s_and_b32 s38, s4, 0x60
	s_add_i32 s75, s74, s7
	s_mov_b64 s[24:25], 0x80
	s_lshl_b32 s3, s63, 6
	s_lshl_b32 s6, s63, 13
	s_lshl_b32 s8, s38, 7
	v_lshl_add_u64 v[8:9], v[8:9], 0, s[24:25]
	s_mov_b32 m0, s75
	s_add_i32 s76, s75, 0x2000
	s_add_i32 s77, s68, 0x8000
	s_add_i32 s78, s68, 0xa000
	global_load_lds_dwordx4 v[8:9], off
	v_lshl_add_u64 v[6:7], v[6:7], 0, s[24:25]
	s_mov_b32 m0, s76
	s_add_u32 s4, s50, 0x80080
	global_load_lds_dwordx4 v[6:7], off
	v_lshl_add_u64 v[2:3], v[2:3], 0, s[24:25]
	s_mov_b32 m0, s77
	s_addc_u32 s5, s51, 0
	s_add_i32 s79, s14, 0x1c000
	global_load_lds_dwordx4 v[2:3], off
	v_lshl_add_u64 v[2:3], v[4:5], 0, s[24:25]
	s_mov_b32 m0, s78
	s_add_i32 s80, s79, s7
	global_load_lds_dwordx4 v[2:3], off
	v_lshl_add_u64 v[2:3], s[4:5], 0, v[196:197]
	s_mov_b32 m0, s80
	s_add_i32 s81, s80, 0x2000
	global_load_lds_dwordx4 v[2:3], off
	v_lshl_add_u64 v[2:3], s[4:5], 0, v[200:201]
	s_mov_b32 m0, s81
	v_and_b32_e32 v202, 15, v1
	global_load_lds_dwordx4 v[2:3], off
	v_lshrrev_b32_e32 v2, 1, v1
	v_and_b32_e32 v2, 24, v2
	v_lshlrev_b32_e32 v3, 1, v2
	v_lshlrev_b32_e32 v1, 2, v1
	v_or_b32_e32 v203, s38, v2
	v_lshlrev_b32_e32 v2, 15, v13
	v_lshl_or_b32 v3, v202, 6, v3
	v_and_b32_e32 v1, 32, v1
	v_and_b32_e32 v2, 0xffff0000, v2
	v_bitop3_b32 v4, v3, s6, v1 bitop3:0xde
	v_bitop3_b32 v1, v3, s8, v1 bitop3:0xde
	v_lshl_add_u32 v2, v14, 12, v2
	v_and_b32_e32 v3, 1, v13
	v_lshl_or_b32 v2, v3, 6, v2
	s_mov_b64 s[36:37], 0x80080
	v_lshl_add_u32 v2, v15, 1, v2
	v_mov_b32_e32 v3, v197
	s_cmpk_lt_u32 s2, 0x100
	v_lshl_add_u64 v[208:209], v[2:3], 0, s[36:37]
	v_lshlrev_b32_e32 v2, 15, v10
	s_cselect_b64 s[26:27], -1, 0
	s_ashr_i32 s2, s3, 31
	s_ashr_i32 s82, s33, 31
	s_ashr_i32 s83, s58, 31
	v_and_b32_e32 v2, 0xffff0000, v2
	s_add_u32 s28, s15, 0x16000
	v_lshl_add_u32 v2, v11, 12, v2
	v_and_b32_e32 v3, 1, v10
	s_waitcnt vmcnt(8)
	s_barrier
	s_waitcnt vmcnt(6)
	s_addc_u32 s29, s31, 0
	v_lshl_or_b32 v2, v3, 6, v2
	s_add_u32 s30, s15, 0x1b800
	v_lshl_add_u32 v2, v12, 1, v2
	v_mov_b32_e32 v3, v197
	v_or_b32_e32 v204, s3, v202
	v_mov_b32_e32 v205, s2
	v_cmp_eq_u32_e64 s[2:3], 15, v202
	s_mov_b32 s48, 0
	v_cmp_eq_u32_e64 s[4:5], 0, v202
	v_cmp_ne_u32_e64 s[6:7], 15, v202
	v_cmp_ne_u32_e64 s[8:9], 0, v202
	v_cmp_gt_u32_e64 s[10:11], 2, v202
	v_cmp_lt_u32_e64 s[12:13], 13, v202
	v_add_u32_e32 v206, -12, v202
	v_mov_b32_e32 v207, v197
	s_addc_u32 s31, s31, 0
	v_lshl_add_u64 v[210:211], v[2:3], 0, s[36:37]
	v_mov_b64_e32 v[212:213], 0xb00
	v_mov_b64_e32 v[214:215], 0xaff
	s_movk_i32 s84, 0x161
	v_add_u32_e32 v228, s34, v1
	v_add_u32_e32 v229, s35, v1
	v_add_u32_e32 v231, s14, v4
	s_movk_i32 s85, 0x2c00
	s_mov_b32 s86, 0x2c000
	s_mov_b32 s87, 0x58000
	s_mov_b32 s88, 0x18c000
	s_mov_b32 s89, 0x1b8000
	v_mov_b32_e32 v232, 0x2c00
	s_barrier
	s_branch .LBB0_2552

.LBB0_2723:
	s_add_u32 s6, s6, 0xe600000
	s_addc_u32 s7, s7, 0
	s_lshl_b32 s8, s8, 5
	s_add_i32 s48, s12, 0x18000
	s_and_b32 s16, s8, 0x60
	s_add_i32 s49, s48, s11
	s_mov_b64 s[8:9], 0x80
	s_lshl_b32 s13, s0, 13
	s_lshl_b32 s17, s16, 7
	v_lshl_add_u64 v[8:9], v[8:9], 0, s[8:9]
	s_mov_b32 m0, s49
	s_add_i32 s50, s49, 0x2000
	s_add_i32 s51, s44, 0x8000
	s_add_i32 s52, s44, 0xa000
	global_load_lds_dwordx4 v[8:9], off
	v_lshl_add_u64 v[6:7], v[6:7], 0, s[8:9]
	s_mov_b32 m0, s50
	s_add_u32 s14, s26, 0x160080
	global_load_lds_dwordx4 v[6:7], off
	v_lshl_add_u64 v[2:3], v[2:3], 0, s[8:9]
	s_mov_b32 m0, s51
	s_addc_u32 s15, s27, 0
	s_add_i32 s53, s12, 0x1c000
	global_load_lds_dwordx4 v[2:3], off
	v_lshl_add_u64 v[2:3], v[4:5], 0, s[8:9]
	s_mov_b32 m0, s52
	s_add_i32 s54, s53, s11
	global_load_lds_dwordx4 v[2:3], off
	v_lshl_add_u64 v[2:3], s[14:15], 0, v[196:197]
	s_mov_b32 m0, s54
	s_add_i32 s55, s54, 0x2000
	global_load_lds_dwordx4 v[2:3], off
	v_lshl_add_u64 v[2:3], s[14:15], 0, v[200:201]
	s_mov_b32 m0, s55
	s_mov_b64 s[14:15], 0x160080
	global_load_lds_dwordx4 v[2:3], off
	v_lshrrev_b32_e32 v3, 1, v10
	v_and_b32_e32 v3, 24, v3
	v_and_b32_e32 v2, 15, v10
	v_lshlrev_b32_e32 v4, 1, v3
	v_lshl_or_b32 v1, s0, 6, v2
	v_lshl_or_b32 v2, v2, 6, v4
	v_lshlrev_b32_e32 v4, 2, v10
	v_and_b32_e32 v4, 32, v4
	v_bitop3_b32 v5, v2, s13, v4 bitop3:0xde
	v_bitop3_b32 v222, v2, s17, v4 bitop3:0xde
	v_or_b32_e32 v223, s16, v3
	v_lshrrev_b32_e32 v3, 1, v15
	v_mul_lo_u32 v2, v17, s1
	s_mov_b32 s0, 0x16000
	v_mad_u64_u32 v[2:3], s[16:17], v3, s0, v[2:3]
	v_or_b32_e32 v2, v2, v16
	v_add_lshl_u32 v2, v2, v18, 1
	v_mov_b32_e32 v3, v197
	v_lshl_add_u64 v[202:203], v[2:3], 0, s[14:15]
	v_lshrrev_b32_e32 v3, 1, v11
	v_mul_lo_u32 v2, v12, s1
	v_mad_u64_u32 v[2:3], s[0:1], v3, s0, v[2:3]
	s_waitcnt vmcnt(8)
	s_barrier
	s_waitcnt vmcnt(6)
	v_or_b32_e32 v2, v2, v13
	s_cmpk_lt_u32 s10, 0x100
	v_add_lshl_u32 v2, v2, v14, 1
	v_mov_b32_e32 v3, v197
	s_cselect_b64 s[10:11], -1, 0
	s_ashr_i32 s56, s33, 31
	s_ashr_i32 s57, s72, 31
	v_lshl_add_u64 v[204:205], v[2:3], 0, s[14:15]
	s_mov_b32 s24, 0
	v_mov_b64_e32 v[206:207], 0x200
	v_mov_b64_e32 v[208:209], 0x1ff
	v_add_u32_e32 v224, s2, v222
	v_add_u32_e32 v225, s3, v222
	v_add_u32_e32 v226, s12, v5
	s_mov_b64 s[12:13], 0x80000
	s_mov_b32 s58, 0x80000
	s_mov_b64 s[14:15], 0x90000
	s_mov_b32 s59, 0x90000
	s_mov_b64 s[16:17], 0xa0000
	s_mov_b32 s60, 0xa0000
	s_mov_b64 s[18:19], 0xb0000
	s_mov_b32 s61, 0xb0000
	s_barrier
	s_waitcnt vmcnt(0)
	s_branch .LBB0_2726
